# baseline (speedup 1.0000x reference)
; #define STAGE_A(Pp, br, kt) do { const char* _g = (const char*)(A + (size_t)(br) * lda + a_col(amode, kt)); \
;     __builtin_amdgcn_global_load_lds((const unsigned*)(_g + aoffb), (LAS unsigned*)((Pp) + tid * 16), 16, 0, 0); \
;     __builtin_amdgcn_global_load_lds((const unsigned*)(_g + (size_t)128 * lda + aoffb), (LAS unsigned*)((Pp) + tid * 16 + 8192), 16, 0, 0); } while (0)
; #define STAGE_B(Pp, br, kt) do { const char* _g = (const char*)(Bt + (size_t)(br) * K + (kt) * BK); \
;     __builtin_amdgcn_global_load_lds((const unsigned*)(_g + boffb), (LAS unsigned*)((Pp) + tid * 16), 16, 0, 0); \
;     __builtin_amdgcn_global_load_lds((const unsigned*)(_g + (size_t)128 * K + boffb), (LAS unsigned*)((Pp) + tid * 16 + 8192), 16, 0, 0); } while (0)
; #define LDA(dst, b, h) for (int m = 0; m < 4; ++m) for (int k = 0; k < 2; ++k) dst[m][k] = *(const LAS bf16x8*)(SA(b, h) + lds_byte(wr * 64 + m * 16 + fr, k * 32 + fq * 8))
; #define LDB(dst, b, h) for (int n = 0; n < 2; ++n) for (int k = 0; k < 2; ++k) dst[n][k] = *(const LAS bf16x8*)(SB(b, h) + lds_byte(wc * 32 + n * 16 + fr, k * 32 + fq * 8))
; #define MMA(ai, bj, At_, Bt_) do { __builtin_amdgcn_s_setprio(1); \
;     for (int m = 0; m < 4; ++m) for (int n = 0; n < 2; ++n) for (int k = 0; k < 2; ++k) \
;         acc[ai][bj][m][n] = MFMA16(Bt_[n][k], At_[m][k], acc[ai][bj][m][n]); \
;     __builtin_amdgcn_s_setprio(0); } while (0)
; #define WAIT_V(n) asm volatile("s_waitcnt vmcnt(" #n ")" ::: "memory")
; #define WAIT_L(n) asm volatile("s_waitcnt lgkmcnt(" #n ")" ::: "memory")
; #define BAR __builtin_amdgcn_s_barrier()
; #define SCHED __builtin_amdgcn_sched_barrier(0)
; DI void gemm_phase(const Params& P, const GemmJob& J, LAS unsigned char* lds) {
;     ...
;             for (int t = 0; t < nt; t += 2) {
;                 const bool last = (t == nt - 2);
;                 const int r2 = last ? brow2 : brow, c2 = last ? bcol2 : bcol, k2 = last ? 0 : t + 2, k3 = k2 + 1;
;                 LDB(B0, 0, 0); LDB(B1, 0, 1); SCHED; LDA(At, 0, 0); STAGE_A(SA(1, 1), brow + HALF, t + 1);
;                 WAIT_V(8); WAIT_L(0); BAR; MMA(0, 0, At, B0); MMA(0, 1, At, B1); BAR; SCHED;
;                 LDA(At, 0, 1); STAGE_B(SB(0, 0), c2, k2); STAGE_B(SB(0, 1), c2 + HALF, k2); STAGE_A(SA(0, 0), r2, k2);
.LBB0_320:
	ds_read_b128 v[132:135], v151
	ds_read_b128 v[158:161], v151 offset:1024
	ds_read_b128 v[162:165], v151 offset:2048
	ds_read_b128 v[166:169], v151 offset:3072
	ds_read_b128 v[170:173], v152
	ds_read_b128 v[174:177], v152 offset:1024
	ds_read_b128 v[178:181], v152 offset:2048
	ds_read_b128 v[186:189], v152 offset:3072
	s_add_i32 s20, s97, -2
	s_cmp_eq_u32 s45, s97
	s_cselect_b32 s42, s94, s36
	s_cselect_b32 s98, s2, s37
	s_cselect_b32 s99, 0, s97
	s_lshl_b32 s28, s42, 8
	s_cmp_gt_u32 s20, 15
	s_cselect_b32 s20, s39, 0x400
	s_and_b64 vcc, s[4:5], exec
	s_cselect_b32 s20, s20, 0
	s_and_b64 vcc, s[48:49], exec
	s_cselect_b32 s29, s95, 0
	s_add_i32 s20, s20, s29
	s_add_i32 vcc_lo, s96, s20
	s_ashr_i32 vcc_hi, vcc_lo, 31
	s_lshl_b64 vcc, vcc, 1
	s_add_u32 vcc_lo, s3, vcc_lo
	s_addc_u32 vcc_hi, s89, vcc_hi
	v_add_u32_e32 v184, s47, v150
	s_add_i32 m0, s100, 0xc000
	ds_read_b128 v[190:193], v153
	ds_read_b128 v[208:211], v153 offset:1024
	ds_read_b128 v[212:215], v184
	ds_read_b128 v[216:219], v184 offset:1024
	ds_read_b128 v[220:223], v154
	ds_read_b128 v[224:227], v154 offset:1024
	ds_read_b128 v[228:231], v155
	ds_read_b128 v[232:235], v155 offset:1024
	global_load_lds_dwordx4 v130, vcc
	s_add_u32 vcc_lo, vcc_lo, s52
	s_addc_u32 vcc_hi, vcc_hi, s53
	s_add_i32 m0, s100, 0xe000
	s_nop 0
	global_load_lds_dwordx4 v130, vcc
	s_waitcnt vmcnt(8)
	s_waitcnt lgkmcnt(0)
	s_barrier
	s_setprio 1
	s_waitcnt lgkmcnt(0)
	v_mfma_f32_16x16x32_bf16 v[124:127], v[132:135], v[190:193], v[124:127]
	v_mfma_f32_16x16x32_bf16 v[116:119], v[162:165], v[190:193], v[116:119]
	v_mfma_f32_16x16x32_bf16 v[108:111], v[132:135], v[212:215], v[108:111]
	v_mfma_f32_16x16x32_bf16 v[100:103], v[162:165], v[212:215], v[100:103]
	v_mfma_f32_16x16x32_bf16 v[92:95], v[132:135], v[220:223], v[92:95]
	v_mfma_f32_16x16x32_bf16 v[84:87], v[162:165], v[220:223], v[84:87]
	v_mfma_f32_16x16x32_bf16 v[76:79], v[132:135], v[228:231], v[76:79]
	v_mfma_f32_16x16x32_bf16 v[68:71], v[162:165], v[228:231], v[68:71]
	v_mfma_f32_16x16x32_bf16 v[124:127], v[158:161], v[208:211], v[124:127]
	v_mfma_f32_16x16x32_bf16 v[116:119], v[166:169], v[208:211], v[116:119]
	v_mfma_f32_16x16x32_bf16 v[108:111], v[158:161], v[216:219], v[108:111]
	v_mfma_f32_16x16x32_bf16 v[100:103], v[166:169], v[216:219], v[100:103]
	v_mfma_f32_16x16x32_bf16 v[92:95], v[158:161], v[224:227], v[92:95]
	v_mfma_f32_16x16x32_bf16 v[84:87], v[166:169], v[224:227], v[84:87]
	v_mfma_f32_16x16x32_bf16 v[76:79], v[158:161], v[232:235], v[76:79]
	v_mfma_f32_16x16x32_bf16 v[68:71], v[166:169], v[232:235], v[68:71]
	s_setprio 0
	s_setprio 1
	v_mfma_f32_16x16x32_bf16 v[120:123], v[170:173], v[190:193], v[120:123]
	v_mfma_f32_16x16x32_bf16 v[112:115], v[178:181], v[190:193], v[112:115]
	v_mfma_f32_16x16x32_bf16 v[104:107], v[170:173], v[212:215], v[104:107]
	v_mfma_f32_16x16x32_bf16 v[96:99], v[178:181], v[212:215], v[96:99]
	v_mfma_f32_16x16x32_bf16 v[88:91], v[170:173], v[220:223], v[88:91]
	v_mfma_f32_16x16x32_bf16 v[80:83], v[178:181], v[220:223], v[80:83]
	v_mfma_f32_16x16x32_bf16 v[72:75], v[170:173], v[228:231], v[72:75]
	v_mfma_f32_16x16x32_bf16 v[64:67], v[178:181], v[228:231], v[64:67]
	v_mfma_f32_16x16x32_bf16 v[120:123], v[174:177], v[208:211], v[120:123]
	v_mfma_f32_16x16x32_bf16 v[112:115], v[186:189], v[208:211], v[112:115]
	v_mfma_f32_16x16x32_bf16 v[104:107], v[174:177], v[216:219], v[104:107]
	v_mfma_f32_16x16x32_bf16 v[96:99], v[186:189], v[216:219], v[96:99]
	v_mfma_f32_16x16x32_bf16 v[88:91], v[174:177], v[224:227], v[88:91]
	v_mfma_f32_16x16x32_bf16 v[80:83], v[186:189], v[224:227], v[80:83]
	v_mfma_f32_16x16x32_bf16 v[72:75], v[174:177], v[232:235], v[72:75]
	v_mfma_f32_16x16x32_bf16 v[64:67], v[186:189], v[232:235], v[64:67]
	s_setprio 0
	s_barrier
	s_ashr_i32 s20, s28, 31
	s_mul_i32 s29, s20, s46
	s_mul_hi_u32 s20, s28, s46
	s_add_i32 vcc_hi, s20, s29
	s_mul_i32 vcc_lo, s28, s46
	s_lshl_b64 vcc, vcc, 1
	s_add_u32 s42, s8, vcc_lo
	s_addc_u32 s43, s9, vcc_hi
	s_lshl_b32 s20, s99, 6
	s_lshl_b64 vcc, s[20:21], 1
	s_add_u32 s42, s42, vcc_lo
	s_addc_u32 s43, s43, vcc_hi
	v_lshl_add_u64 v[182:183], s[42:43], 0, v[128:129]
	s_add_u32 s42, s42, s50
	s_addc_u32 s43, s43, s51
	s_add_i32 m0, s100, 0x10000
	v_lshl_add_u64 v[236:237], s[42:43], 0, v[128:129]
	s_bitset1_b32 s28, 7
	ds_read_b128 v[190:193], v153 offset:16384
	ds_read_b128 v[208:211], v153 offset:17408
	ds_read_b128 v[212:215], v184 offset:16384
	ds_read_b128 v[216:219], v184 offset:17408
	ds_read_b128 v[220:223], v154 offset:16384
	ds_read_b128 v[224:227], v154 offset:17408
	ds_read_b128 v[228:231], v155 offset:16384
	ds_read_b128 v[232:235], v155 offset:17408
	global_load_lds_dwordx4 v[182:183], off
	s_add_i32 m0, s100, 0x12000
	s_mul_hi_u32 s42, s28, s46
	s_add_i32 s43, s42, s29
	s_mul_i32 s42, s28, s46
	s_lshl_b64 s[42:43], s[42:43], 1
	s_add_u32 s28, s8, s42
	s_addc_u32 s29, s9, s43
	s_add_u32 s42, s28, vcc_lo
	s_addc_u32 s43, s29, vcc_hi
	global_load_lds_dwordx4 v[236:237], off
	v_lshl_add_u64 v[238:239], s[42:43], 0, v[128:129]
	s_add_i32 m0, s100, 0x14000
	s_add_u32 s42, s42, s50
	s_addc_u32 s43, s43, s51
	global_load_lds_dwordx4 v[238:239], off
	s_add_i32 m0, s100, 0x16000
	s_ashr_i32 s28, s98, 31
	s_mul_i32 s28, s28, s44
	s_mul_hi_u32 s29, s98, s44
	v_lshl_add_u64 v[240:241], s[42:43], 0, v[128:129]
	s_add_i32 s43, s29, s28
	s_mul_i32 s42, s98, s44
	s_lshl_b64 s[42:43], s[42:43], 1
	s_add_u32 s29, s10, s42
	s_addc_u32 s85, s11, s43
	s_cmp_gt_u32 s99, 15
	s_cselect_b32 vcc_lo, s39, 0x400
	s_and_b64 s[42:43], s[4:5], exec
	s_cselect_b32 vcc_lo, vcc_lo, 0
	s_lshl_b32 s99, s99, 5
	s_and_b64 s[42:43], s[48:49], exec
	s_cselect_b32 s42, s99, 0
	s_add_i32 s42, vcc_lo, s42
	s_add_i32 s20, s42, s20
	s_lshl_b64 s[42:43], s[20:21], 1
	s_add_u32 vcc_lo, s29, s42
	s_addc_u32 vcc_hi, s85, s43
	global_load_lds_dwordx4 v[240:241], off
	s_mov_b32 m0, s100
	s_nop 0
	global_load_lds_dwordx4 v130, vcc
	s_add_u32 vcc_lo, vcc_lo, s52
	s_addc_u32 vcc_hi, vcc_hi, s53
	s_add_i32 m0, s100, 0x2000
	s_nop 0
	global_load_lds_dwordx4 v130, vcc
	s_waitcnt vmcnt(8)
	s_waitcnt lgkmcnt(0)
	s_barrier
; #define STAGE_A(Pp, br, kt) do { const char* _g = (const char*)(A + (size_t)(br) * lda + a_col(amode, kt)); \
;     __builtin_amdgcn_global_load_lds((const unsigned*)(_g + aoffb), (LAS unsigned*)((Pp) + tid * 16), 16, 0, 0); \
;     __builtin_amdgcn_global_load_lds((const unsigned*)(_g + (size_t)128 * lda + aoffb), (LAS unsigned*)((Pp) + tid * 16 + 8192), 16, 0, 0); } while (0)
; #define LDA(dst, b, h) for (int m = 0; m < 4; ++m) for (int k = 0; k < 2; ++k) dst[m][k] = *(const LAS bf16x8*)(SA(b, h) + lds_byte(wr * 64 + m * 16 + fr, k * 32 + fq * 8))
; #define LDB(dst, b, h) for (int n = 0; n < 2; ++n) for (int k = 0; k < 2; ++k) dst[n][k] = *(const LAS bf16x8*)(SB(b, h) + lds_byte(wc * 32 + n * 16 + fr, k * 32 + fq * 8))
; #define MMA(ai, bj, At_, Bt_) do { __builtin_amdgcn_s_setprio(1); \
;     for (int m = 0; m < 4; ++m) for (int n = 0; n < 2; ++n) for (int k = 0; k < 2; ++k) \
;         acc[ai][bj][m][n] = MFMA16(Bt_[n][k], At_[m][k], acc[ai][bj][m][n]); \
;     __builtin_amdgcn_s_setprio(0); } while (0)
; #define WAIT_V(n) asm volatile("s_waitcnt vmcnt(" #n ")" ::: "memory")
; #define WAIT_L(n) asm volatile("s_waitcnt lgkmcnt(" #n ")" ::: "memory")
; #define BAR __builtin_amdgcn_s_barrier()
; #define SCHED __builtin_amdgcn_sched_barrier(0)
; DI void gemm_phase(const Params& P, const GemmJob& J, LAS unsigned char* lds) {
;     ...
;                 WAIT_V(8); WAIT_L(0); BAR; MMA(1, 0, At, B0); MMA(1, 1, At, B1); BAR; SCHED;
;                 LDB(B0, 1, 0); LDB(B1, 1, 1); SCHED; LDA(At, 1, 0); STAGE_A(SA(0, 1), r2 + HALF, k2);
;                 WAIT_V(8); WAIT_L(0); BAR; MMA(0, 0, At, B0); MMA(0, 1, At, B1); BAR; SCHED;
	s_setprio 1
	s_waitcnt lgkmcnt(0)
	v_mfma_f32_16x16x32_bf16 v[60:63], v[132:135], v[190:193], v[60:63]
	v_mfma_f32_16x16x32_bf16 v[52:55], v[162:165], v[190:193], v[52:55]
	v_mfma_f32_16x16x32_bf16 v[44:47], v[132:135], v[212:215], v[44:47]
	v_mfma_f32_16x16x32_bf16 v[36:39], v[162:165], v[212:215], v[36:39]
	v_mfma_f32_16x16x32_bf16 v[28:31], v[132:135], v[220:223], v[28:31]
	v_mfma_f32_16x16x32_bf16 v[20:23], v[162:165], v[220:223], v[20:23]
	v_mfma_f32_16x16x32_bf16 v[12:15], v[132:135], v[228:231], v[12:15]
	v_mfma_f32_16x16x32_bf16 v[4:7], v[162:165], v[228:231], v[4:7]
	v_mfma_f32_16x16x32_bf16 v[60:63], v[158:161], v[208:211], v[60:63]
	v_mfma_f32_16x16x32_bf16 v[52:55], v[166:169], v[208:211], v[52:55]
	v_mfma_f32_16x16x32_bf16 v[44:47], v[158:161], v[216:219], v[44:47]
	v_mfma_f32_16x16x32_bf16 v[36:39], v[166:169], v[216:219], v[36:39]
	v_mfma_f32_16x16x32_bf16 v[28:31], v[158:161], v[224:227], v[28:31]
	v_mfma_f32_16x16x32_bf16 v[20:23], v[166:169], v[224:227], v[20:23]
	v_mfma_f32_16x16x32_bf16 v[12:15], v[158:161], v[232:235], v[12:15]
	v_mfma_f32_16x16x32_bf16 v[4:7], v[166:169], v[232:235], v[4:7]
	s_setprio 0
	s_setprio 1
	v_mfma_f32_16x16x32_bf16 v[56:59], v[170:173], v[190:193], v[56:59]
	v_mfma_f32_16x16x32_bf16 v[48:51], v[178:181], v[190:193], v[48:51]
	v_mfma_f32_16x16x32_bf16 v[40:43], v[170:173], v[212:215], v[40:43]
	v_mfma_f32_16x16x32_bf16 v[32:35], v[178:181], v[212:215], v[32:35]
	v_mfma_f32_16x16x32_bf16 v[24:27], v[170:173], v[220:223], v[24:27]
	v_mfma_f32_16x16x32_bf16 v[16:19], v[178:181], v[220:223], v[16:19]
	v_mfma_f32_16x16x32_bf16 v[8:11], v[170:173], v[228:231], v[8:11]
	v_mfma_f32_16x16x32_bf16 v[0:3], v[178:181], v[228:231], v[0:3]
	v_mfma_f32_16x16x32_bf16 v[56:59], v[174:177], v[208:211], v[56:59]
	v_mfma_f32_16x16x32_bf16 v[48:51], v[186:189], v[208:211], v[48:51]
	v_mfma_f32_16x16x32_bf16 v[40:43], v[174:177], v[216:219], v[40:43]
	v_mfma_f32_16x16x32_bf16 v[32:35], v[186:189], v[216:219], v[32:35]
	v_mfma_f32_16x16x32_bf16 v[24:27], v[174:177], v[224:227], v[24:27]
	v_mfma_f32_16x16x32_bf16 v[16:19], v[186:189], v[224:227], v[16:19]
	v_mfma_f32_16x16x32_bf16 v[8:11], v[174:177], v[232:235], v[8:11]
	v_mfma_f32_16x16x32_bf16 v[0:3], v[186:189], v[232:235], v[0:3]
	s_setprio 0
	s_barrier
	ds_read_b128 v[132:135], v156
	ds_read_b128 v[158:161], v156 offset:1024
	ds_read_b128 v[162:165], v156 offset:2048
	ds_read_b128 v[166:169], v156 offset:3072
	ds_read_b128 v[170:173], v157
	ds_read_b128 v[174:177], v157 offset:1024
	ds_read_b128 v[178:181], v157 offset:2048
	ds_read_b128 v[186:189], v157 offset:3072
	s_bitset1_b32 s98, 7
	s_mul_hi_u32 s99, s98, s44
	s_add_i32 s99, s99, s28
	s_mul_i32 s98, s98, s44
	s_lshl_b64 s[98:99], s[98:99], 1
	s_add_u32 s28, s10, s98
	s_addc_u32 s98, s11, s99
	s_add_u32 s42, s28, s42
	s_addc_u32 s43, s98, s43
	s_add_i32 m0, s100, 0x4000
	ds_read_b128 v[190:193], v153 offset:32768
	ds_read_b128 v[208:211], v153 offset:33792
	ds_read_b128 v[212:215], v184 offset:32768
	ds_read_b128 v[216:219], v184 offset:33792
	ds_read_b128 v[220:223], v154 offset:32768
	ds_read_b128 v[224:227], v154 offset:33792
	ds_read_b128 v[228:231], v155 offset:32768
	ds_read_b128 v[232:235], v155 offset:33792
	global_load_lds_dwordx4 v130, s[42:43]
	s_add_u32 s42, s42, s52
	s_addc_u32 s43, s43, s53
	s_add_i32 m0, s100, 0x6000
	s_nop 0
	global_load_lds_dwordx4 v130, s[42:43]
	s_waitcnt vmcnt(8)
	s_waitcnt lgkmcnt(0)
	s_barrier
	s_setprio 1
	s_waitcnt lgkmcnt(0)
	v_mfma_f32_16x16x32_bf16 v[124:127], v[132:135], v[190:193], v[124:127]
	v_mfma_f32_16x16x32_bf16 v[116:119], v[162:165], v[190:193], v[116:119]
	v_mfma_f32_16x16x32_bf16 v[108:111], v[132:135], v[212:215], v[108:111]
	v_mfma_f32_16x16x32_bf16 v[100:103], v[162:165], v[212:215], v[100:103]
	v_mfma_f32_16x16x32_bf16 v[92:95], v[132:135], v[220:223], v[92:95]
	v_mfma_f32_16x16x32_bf16 v[84:87], v[162:165], v[220:223], v[84:87]
	v_mfma_f32_16x16x32_bf16 v[76:79], v[132:135], v[228:231], v[76:79]
	v_mfma_f32_16x16x32_bf16 v[68:71], v[162:165], v[228:231], v[68:71]
	v_mfma_f32_16x16x32_bf16 v[124:127], v[158:161], v[208:211], v[124:127]
	v_mfma_f32_16x16x32_bf16 v[116:119], v[166:169], v[208:211], v[116:119]
	v_mfma_f32_16x16x32_bf16 v[108:111], v[158:161], v[216:219], v[108:111]
	v_mfma_f32_16x16x32_bf16 v[100:103], v[166:169], v[216:219], v[100:103]
	v_mfma_f32_16x16x32_bf16 v[92:95], v[158:161], v[224:227], v[92:95]
	v_mfma_f32_16x16x32_bf16 v[84:87], v[166:169], v[224:227], v[84:87]
	v_mfma_f32_16x16x32_bf16 v[76:79], v[158:161], v[232:235], v[76:79]
	v_mfma_f32_16x16x32_bf16 v[68:71], v[166:169], v[232:235], v[68:71]
	s_setprio 0
	s_setprio 1
	v_mfma_f32_16x16x32_bf16 v[120:123], v[170:173], v[190:193], v[120:123]
	v_mfma_f32_16x16x32_bf16 v[112:115], v[178:181], v[190:193], v[112:115]
	v_mfma_f32_16x16x32_bf16 v[104:107], v[170:173], v[212:215], v[104:107]
	v_mfma_f32_16x16x32_bf16 v[96:99], v[178:181], v[212:215], v[96:99]
	v_mfma_f32_16x16x32_bf16 v[88:91], v[170:173], v[220:223], v[88:91]
	v_mfma_f32_16x16x32_bf16 v[80:83], v[178:181], v[220:223], v[80:83]
	v_mfma_f32_16x16x32_bf16 v[72:75], v[170:173], v[228:231], v[72:75]
	v_mfma_f32_16x16x32_bf16 v[64:67], v[178:181], v[228:231], v[64:67]
	v_mfma_f32_16x16x32_bf16 v[120:123], v[174:177], v[208:211], v[120:123]
	v_mfma_f32_16x16x32_bf16 v[112:115], v[186:189], v[208:211], v[112:115]
	v_mfma_f32_16x16x32_bf16 v[104:107], v[174:177], v[216:219], v[104:107]
	v_mfma_f32_16x16x32_bf16 v[96:99], v[186:189], v[216:219], v[96:99]
	v_mfma_f32_16x16x32_bf16 v[88:91], v[174:177], v[224:227], v[88:91]
	v_mfma_f32_16x16x32_bf16 v[80:83], v[186:189], v[224:227], v[80:83]
	v_mfma_f32_16x16x32_bf16 v[72:75], v[174:177], v[232:235], v[72:75]
	v_mfma_f32_16x16x32_bf16 v[64:67], v[186:189], v[232:235], v[64:67]
	s_setprio 0
	s_barrier
; #define STAGE_A(Pp, br, kt) do { const char* _g = (const char*)(A + (size_t)(br) * lda + a_col(amode, kt)); \
;     __builtin_amdgcn_global_load_lds((const unsigned*)(_g + aoffb), (LAS unsigned*)((Pp) + tid * 16), 16, 0, 0); \
;     __builtin_amdgcn_global_load_lds((const unsigned*)(_g + (size_t)128 * lda + aoffb), (LAS unsigned*)((Pp) + tid * 16 + 8192), 16, 0, 0); } while (0)
; #define STAGE_B(Pp, br, kt) do { const char* _g = (const char*)(Bt + (size_t)(br) * K + (kt) * BK); \
;     __builtin_amdgcn_global_load_lds((const unsigned*)(_g + boffb), (LAS unsigned*)((Pp) + tid * 16), 16, 0, 0); \
;     __builtin_amdgcn_global_load_lds((const unsigned*)(_g + (size_t)128 * K + boffb), (LAS unsigned*)((Pp) + tid * 16 + 8192), 16, 0, 0); } while (0)
; #define LDA(dst, b, h) for (int m = 0; m < 4; ++m) for (int k = 0; k < 2; ++k) dst[m][k] = *(const LAS bf16x8*)(SA(b, h) + lds_byte(wr * 64 + m * 16 + fr, k * 32 + fq * 8))
; #define MMA(ai, bj, At_, Bt_) do { __builtin_amdgcn_s_setprio(1); \
;     for (int m = 0; m < 4; ++m) for (int n = 0; n < 2; ++n) for (int k = 0; k < 2; ++k) \
;         acc[ai][bj][m][n] = MFMA16(Bt_[n][k], At_[m][k], acc[ai][bj][m][n]); \
;     __builtin_amdgcn_s_setprio(0); } while (0)
; #define WAIT_V(n) asm volatile("s_waitcnt vmcnt(" #n ")" ::: "memory")
; #define WAIT_L(n) asm volatile("s_waitcnt lgkmcnt(" #n ")" ::: "memory")
; #define BAR __builtin_amdgcn_s_barrier()
; #define SCHED __builtin_amdgcn_sched_barrier(0)
; DI void gemm_phase(const Params& P, const GemmJob& J, LAS unsigned char* lds) {
;     ...
;                 LDA(At, 1, 1); STAGE_B(SB(1, 0), c2, k3); STAGE_B(SB(1, 1), c2 + HALF, k3); STAGE_A(SA(1, 0), r2, k3);
;                 WAIT_V(8); WAIT_L(0); BAR; MMA(1, 0, At, B0); MMA(1, 1, At, B1); BAR; SCHED;
;             }
	s_add_i32 s42, s20, 64
	s_add_i32 m0, s100, 0x17f80
	s_ashr_i32 s43, s42, 31
	ds_read_b128 v[190:193], v153 offset:49152
	ds_read_b128 v[208:211], v153 offset:50176
	ds_read_b128 v[212:215], v184 offset:49152
	ds_read_b128 v[216:219], v184 offset:50176
	ds_read_b128 v[220:223], v154 offset:49152
	ds_read_b128 v[224:227], v154 offset:50176
	ds_read_b128 v[228:231], v155 offset:49152
	ds_read_b128 v[232:235], v155 offset:50176
	global_load_lds_dwordx4 v[182:183], off offset:128
	s_add_i32 m0, s100, 0x19f80
	s_lshl_b64 s[42:43], s[42:43], 1
	global_load_lds_dwordx4 v[236:237], off offset:128
	s_add_i32 m0, s100, 0x1bf80
	s_add_u32 s42, s29, s42
	s_addc_u32 s43, s85, s43
	global_load_lds_dwordx4 v[238:239], off offset:128
	s_add_i32 m0, s100, 0x1df80
	s_nop 0
	global_load_lds_dwordx4 v[240:241], off offset:128
	s_add_i32 m0, s100, 0x8000
	s_nop 0
	global_load_lds_dwordx4 v130, s[42:43]
	s_add_u32 s42, s42, s52
	s_addc_u32 s43, s43, s53
	s_add_i32 m0, s100, 0xa000
	s_nop 0
	global_load_lds_dwordx4 v130, s[42:43]
	s_waitcnt vmcnt(8)
	s_waitcnt lgkmcnt(0)
	s_barrier
	s_setprio 1
	s_waitcnt lgkmcnt(0)
	v_mfma_f32_16x16x32_bf16 v[60:63], v[132:135], v[190:193], v[60:63]
	v_mfma_f32_16x16x32_bf16 v[52:55], v[162:165], v[190:193], v[52:55]
	v_mfma_f32_16x16x32_bf16 v[44:47], v[132:135], v[212:215], v[44:47]
	v_mfma_f32_16x16x32_bf16 v[36:39], v[162:165], v[212:215], v[36:39]
	v_mfma_f32_16x16x32_bf16 v[28:31], v[132:135], v[220:223], v[28:31]
	v_mfma_f32_16x16x32_bf16 v[20:23], v[162:165], v[220:223], v[20:23]
	v_mfma_f32_16x16x32_bf16 v[12:15], v[132:135], v[228:231], v[12:15]
	v_mfma_f32_16x16x32_bf16 v[4:7], v[162:165], v[228:231], v[4:7]
	v_mfma_f32_16x16x32_bf16 v[60:63], v[158:161], v[208:211], v[60:63]
	v_mfma_f32_16x16x32_bf16 v[52:55], v[166:169], v[208:211], v[52:55]
	v_mfma_f32_16x16x32_bf16 v[44:47], v[158:161], v[216:219], v[44:47]
	v_mfma_f32_16x16x32_bf16 v[36:39], v[166:169], v[216:219], v[36:39]
	v_mfma_f32_16x16x32_bf16 v[28:31], v[158:161], v[224:227], v[28:31]
	v_mfma_f32_16x16x32_bf16 v[20:23], v[166:169], v[224:227], v[20:23]
	v_mfma_f32_16x16x32_bf16 v[12:15], v[158:161], v[232:235], v[12:15]
	v_mfma_f32_16x16x32_bf16 v[4:7], v[166:169], v[232:235], v[4:7]
	s_setprio 0
	s_setprio 1
	v_mfma_f32_16x16x32_bf16 v[56:59], v[170:173], v[190:193], v[56:59]
	v_mfma_f32_16x16x32_bf16 v[48:51], v[178:181], v[190:193], v[48:51]
	v_mfma_f32_16x16x32_bf16 v[40:43], v[170:173], v[212:215], v[40:43]
	v_mfma_f32_16x16x32_bf16 v[32:35], v[178:181], v[212:215], v[32:35]
	v_mfma_f32_16x16x32_bf16 v[24:27], v[170:173], v[220:223], v[24:27]
	v_mfma_f32_16x16x32_bf16 v[16:19], v[178:181], v[220:223], v[16:19]
	v_mfma_f32_16x16x32_bf16 v[8:11], v[170:173], v[228:231], v[8:11]
	v_mfma_f32_16x16x32_bf16 v[0:3], v[178:181], v[228:231], v[0:3]
	v_mfma_f32_16x16x32_bf16 v[56:59], v[174:177], v[208:211], v[56:59]
	v_mfma_f32_16x16x32_bf16 v[48:51], v[186:189], v[208:211], v[48:51]
	v_mfma_f32_16x16x32_bf16 v[40:43], v[174:177], v[216:219], v[40:43]
	v_mfma_f32_16x16x32_bf16 v[32:35], v[186:189], v[216:219], v[32:35]
	v_mfma_f32_16x16x32_bf16 v[24:27], v[174:177], v[224:227], v[24:27]
	v_mfma_f32_16x16x32_bf16 v[16:19], v[186:189], v[224:227], v[16:19]
	v_mfma_f32_16x16x32_bf16 v[8:11], v[174:177], v[232:235], v[8:11]
	v_mfma_f32_16x16x32_bf16 v[0:3], v[186:189], v[232:235], v[0:3]
	s_setprio 0
	s_barrier
	s_add_i32 s95, s95, 64
	s_addk_i32 s96, 0x80
	s_add_i32 s20, s97, 2
	s_cmp_ge_u32 s97, s45
	s_mov_b32 s97, s20
	s_cbranch_scc0 .LBB0_320
	s_and_b64 vcc, exec, s[56:57]
	s_cbranch_vccz .LBB0_323
	s_barrier
